# v34: as v33 but the static priority raise goes to waves 0-3 instead of 4-7 (which half is the younger one)
# baseline (speedup 1.0000x reference)
; #define LAS __attribute__((address_space(3)))
; __global__ void __launch_bounds__(512, 2) mega_fwd(Args args) {
;     ...
;         __syncthreads();
;         {   LAS unsigned char* vl = lds + wave * (32 * VP);
;             constexpr int NU_S = 32 * 72;
;             for (int u = gw; u < NU_S; u += NGW) {
.LBB0_407:
	s_cmp_lt_u32 s80, 4
	s_cbranch_scc0 .Lp3_prio_done
	s_setprio 1

; #define LAS __attribute__((address_space(3)))
; __device__ __forceinline__ CArgs* phase_args() { CArgs* p = (CArgs*)__builtin_amdgcn_kernarg_segment_ptr(); asm volatile("" : "+s"(p)); return p; }
; __global__ void __launch_bounds__(512, 2) mega_fwd(Args args) {
;     ...
;     if (IN(8)) { CArgs* pa = phase_args();
;         LAS unsigned char* kl = lds; LAS unsigned char* vl2 = lds + 256 * VP;
;         for (int grp0 = bx; grp0 < 256; grp0 += G) { const int grp = (G == 256) ? (grp0 & 7) * 32 + (grp0 >> 3) : grp0; const int h = grp >> 6;
.LBB0_657:
	s_cmp_lt_i32 s24, 9
	s_cselect_b64 s[4:5], -1, 0
	s_cmp_gt_i32 s25, 8
	s_cselect_b64 s[6:7], -1, 0
	s_and_b64 s[4:5], s[4:5], s[6:7]
	s_andn2_b64 vcc, exec, s[4:5]
	s_cbranch_vccnz .LBB0_680
	s_mov_b64 s[8:9], s[0:1]
	s_cmp_lt_u32 s80, 4
	s_cbranch_scc0 .Lp8_prio_done
	s_setprio 1
